# v82 + phase 4: workgroups >=128 (no GLU tile, 14 us of slack) start 10 us late so the critical GLU workgroups run their GLU stage without contention
# speedup vs baseline: 1.0148x; 1.0140x over previous
.LBB0_589:
	s_cmp_gt_i32 s26, 4
	s_cselect_b64 s[4:5], -1, 0
	s_xor_b64 s[0:1], s[0:1], -1
	s_or_b64 s[0:1], s[4:5], s[0:1]
	s_and_b64 vcc, exec, s[0:1]
	s_cbranch_vccnz .LBB0_771
	s_cmpk_lt_u32 s96, 0x80
	s_cbranch_scc1 .Lp4_lag
	s_sleep 127
	s_sleep 127
	s_sleep 127
